# scan L2 prefetch extended to the next chunk's B^T tile (third LDS-DMA dword load per wave; its DMA sits ahead of the x re-read waits in the in-order queue), on top of v064
# baseline (speedup 1.0000x reference)
; #define LAS __attribute__((address_space(3)))
; template <int MODE> __device__ __forceinline__ void ssd_scan_phase(Frame& F, int j, bool ctx_out) {
;     ...
;                     const int l = 16 * lt + fr; const float cl = tab[l];
;                     f32x4 accd[2], acco[2];
;                     accd[0] = accd[1] = acco[0] = acco[1] = (f32x4){0.f, 0.f, 0.f, 0.f};
;                     const int kd = lt >> 1;
;                     if ((lt & 1) == 0) { xb_cur = xb_nxt; if (kd + 1 < 4) xb_nxt = *(const bf16x8*)(xl + (size_t)16 * T + 32 * (kd + 1)); }
;                     const bf16x8 xa = xf[0][kd], xb = xb_cur;
; #pragma unroll
;                     for (int ks = 0; ks < 4; ++ks) {
;                         const bool full = dir == 0 ? (ks < kd) : (ks > kd);
;                         if (full) {
;                             const bf16x8 gf = *(const LAS bf16x8*)(GS + l * 256 + (((4 * ks + fq) ^ fr) << 4));
;                             const float f1 = __builtin_amdgcn_exp2f(cl - tab[dir == 0 ? 32 * ks + 31 : 32 * ks]);
;                             const f32x4 z4 = (f32x4){0.f, 0.f, 0.f, 0.f};
;                             const f32x4 t0 = __builtin_amdgcn_mfma_f32_16x16x32_bf16(xs2[0][ks], gf, z4, 0, 0, 0), t1 = __builtin_amdgcn_mfma_f32_16x16x32_bf16(xs2[1][ks], gf, z4, 0, 0, 0);
;                             accd[0] += t0 * f1; accd[1] += t1 * f1;
;                         }
;                     }
; #pragma unroll
;                     for (int q = 0; q < 4; ++q) {
;                         const u32x2 lo = *(const LAS u32x2*)(CS + l * 256 + (((4 * q + (fq >> 1)) ^ fr) << 4) + (fq & 1) * 8), hi = *(const LAS u32x2*)(CS + l * 256 + (((4 * q + 2 + (fq >> 1)) ^ fr) << 4) + (fq & 1) * 8);
;                         u32x4 c4; c4.x = lo.x; c4.y = lo.y; c4.z = hi.x; c4.w = hi.y; const bf16x8 cfr = __builtin_bit_cast(bf16x8, c4);
;                         acco[0] = __builtin_amdgcn_mfma_f32_16x16x32_bf16(hf[0][q], cfr, acco[0], 0, 0, 0);
;                         acco[1] = __builtin_amdgcn_mfma_f32_16x16x32_bf16(hf[1][q], cfr, acco[1], 0, 0, 0);
;                     }
;                     {
;                         float gg[8]; unpack8(*(const LAS u32x4*)(GS + l * 256 + (((4 * kd + fq) ^ fr) << 4)), gg);
;                         const f32x4 ca = *(const LAS f32x4*)(tab + 32 * kd + 8 * fq), cb = *(const LAS f32x4*)(tab + 32 * kd + 8 * fq + 4);
.LBB0_514:
	v_mbcnt_lo_u32_b32 v179, -1, 0
	v_mbcnt_hi_u32_b32 v179, -1, v179
	s_sub_i32 s100, s4, 1
	s_sub_i32 s101, 16, s4
	s_cmp_lg_u32 s38, 0
	s_cselect_b32 s101, s100, s101
	s_lshl_b32 s100, s101, 7
	s_add_i32 s100, s100, s81
	s_cmp_eq_u32 s4, 0
	s_cselect_b32 s100, s76, s100
	s_cselect_b32 s101, 0, s101
	s_cmp_eq_u32 s4, 17
	s_cselect_b32 s100, s81, s100
	s_cselect_b32 s101, 0, s101
	v_and_b32_e32 v178, 3, v179
	v_lshl_add_u32 v178, v178, 5, v188
	v_and_b32_e32 v179, 4, v179
	v_lshlrev_b32_e32 v220, 12, v178
	v_lshl_add_u32 v220, v179, 5, v220
	s_lshl_b32 s101, s101, 8
	v_add_u32_e32 v220, s101, v220
	v_lshlrev_b32_e32 v178, 11, v178
	v_lshl_add_u32 v178, v179, 5, v178
	s_lshl_b32 s100, s100, 11
	v_add_u32_e32 v178, s100, v178
	s_mov_b32 m0, 0x1c000
	s_mov_b32 s100, s77
	s_mov_b32 s101, s73
	global_load_lds_dword v178, s[100:101]
	global_load_lds_dword v178, s[74:75]
	global_load_lds_dword v220, s[10:11]
	v_add3_u32 v178, 0, v218, v195
	v_add_u32_e32 v179, v178, v185
	ds_read_b64 v[218:219], v179
	v_add_u32_e32 v179, v178, v183
	ds_read_b64 v[220:221], v179
	v_add_u32_e32 v179, v178, v187
	ds_read_b64 v[226:227], v179
	v_add_u32_e32 v179, v178, v213
	ds_read_b64 v[228:229], v179
	s_waitcnt lgkmcnt(2)
	v_mfma_f32_16x16x32_bf16 v[222:225], v[116:119], v[218:221], 0
	v_add_u32_e32 v179, v178, v212
	ds_read_b64 v[230:231], v179
	v_add_u32_e32 v179, v178, v211
	v_mfma_f32_16x16x32_bf16 v[218:221], v[124:127], v[218:221], 0
	ds_read_b64 v[232:233], v179
	v_add_u32_e32 v179, v178, v191
	v_add_u32_e32 v178, v178, v210
	s_waitcnt lgkmcnt(2)
	v_mfma_f32_16x16x32_bf16 v[222:225], v[112:115], v[226:229], v[222:225]
	v_add_u32_e32 v170, v170, v168
	v_sub_f32_e32 v164, v171, v164
	v_exp_f32_e32 v164, v164
	v_mfma_f32_16x16x32_bf16 v[218:221], v[120:123], v[226:229], v[218:221]
	ds_read_b64 v[226:227], v179
	ds_read_b64 v[228:229], v178
	v_sub_f32_e32 v165, v171, v165
	s_waitcnt lgkmcnt(2)
	v_mfma_f32_16x16x32_bf16 v[222:225], v[108:111], v[230:233], v[222:225]
	v_exp_f32_e32 v165, v165
	v_sub_f32_e32 v166, v171, v166
	v_exp_f32_e32 v166, v166
	v_mfma_f32_16x16x32_bf16 v[218:221], v[128:131], v[230:233], v[218:221]
	ds_read_b128 v[230:233], v170
	v_add_u32_e32 v170, 64, v180
	s_waitcnt lgkmcnt(1)
	v_mfma_f32_16x16x32_bf16 v[222:225], v[104:107], v[226:229], v[222:225]
	s_waitcnt lgkmcnt(0)
; #define LAS __attribute__((address_space(3)))
; __device__ __forceinline__ unsigned cvt_pk_bf16(float lo, float hi) { const f32x2 v = {lo, hi}; return __builtin_bit_cast(unsigned, __builtin_convertvector(v, bf16x2_t)); }
; __device__ __forceinline__ u32x4 pack8(const float (&f)[8]) { u32x4 w; w.x = cvt_pk_bf16(f[0], f[1]); w.y = cvt_pk_bf16(f[2], f[3]); w.z = cvt_pk_bf16(f[4], f[5]); w.w = cvt_pk_bf16(f[6], f[7]); return w; }
; template <int MODE> __device__ __forceinline__ void ssd_scan_phase(Frame& F, int j, bool ctx_out) {
;     ...
;                         float gg[8]; unpack8(*(const LAS u32x4*)(GS + l * 256 + (((4 * kd + fq) ^ fr) << 4)), gg);
;                         const f32x4 ca = *(const LAS f32x4*)(tab + 32 * kd + 8 * fq), cb = *(const LAS f32x4*)(tab + 32 * kd + 8 * fq + 4);
;                         const f32x4 da = *(const LAS f32x4*)(tab + 128 + 32 * kd + 8 * fq), db = *(const LAS f32x4*)(tab + 128 + 32 * kd + 8 * fq + 4);
;                         const float cs[8] = {ca.x, ca.y, ca.z, ca.w, cb.x, cb.y, cb.z, cb.w}, ds[8] = {da.x, da.y, da.z, da.w, db.x, db.y, db.z, db.w};
;                         float m[8];
; #pragma unroll
;                         for (int jj = 0; jj < 8; ++jj) { const int s = 32 * kd + 8 * fq + jj; const bool valid = dir == 0 ? (s <= l) : (s >= l);
;                             const float e = valid ? __builtin_amdgcn_exp2f(cl - cs[jj]) : 0.f; m[jj] = gg[jj] * e * ds[jj]; if (dir == 0 && s == l) m[jj] += dsk; }
;                         const bf16x8 mf = __builtin_bit_cast(bf16x8, pack8(m));
;                         accd[0] = __builtin_amdgcn_mfma_f32_16x16x32_bf16(xa, mf, accd[0], 0, 0, 0);
;                         accd[1] = __builtin_amdgcn_mfma_f32_16x16x32_bf16(xb, mf, accd[1], 0, 0, 0);
;                     }
;                     const float el = __builtin_amdgcn_exp2f(cl);
; #pragma unroll
;                     for (int pt = 0; pt < 2; ++pt) { const f32x4 y = accd[pt] + acco[pt] * el; u32x2 o; o.x = cvt_pk_bf16(y[0], y[1]); o.y = cvt_pk_bf16(y[2], y[3]);
;                         *(u32x2*)(yout + (size_t)(row0 + l) * DI + h * 64 + ph * 32 + 16 * pt + 4 * fq) = o; }
;                 }
	v_lshlrev_b32_e32 v178, 16, v230
	v_and_b32_e32 v179, 0xffff0000, v230
	v_lshlrev_b32_e32 v230, 16, v233
	v_mfma_f32_16x16x32_bf16 v[218:221], v[132:135], v[226:229], v[218:221]
	v_lshlrev_b32_e32 v226, 16, v231
	v_and_b32_e32 v227, 0xffff0000, v231
	v_lshlrev_b32_e32 v228, 16, v232
	v_and_b32_e32 v229, 0xffff0000, v232
	v_and_b32_e32 v231, 0xffff0000, v233
	v_cmp_le_i32_e32 vcc, v170, v169
	v_cmp_eq_u32_e64 s[100:101], v170, v169
	s_xnor_b64 vcc, vcc, s[38:39]
	s_andn2_b64 s[100:101], s[100:101], s[38:39]
	s_or_b64 vcc, vcc, s[100:101]
	v_sub_f32_e32 v156, v171, v156
	v_cndmask_b32_e32 v164, 0, v164, vcc
	v_mul_f32_e32 v164, v164, v178
	v_cmp_eq_u32_e32 vcc, v170, v169
	v_mul_f32_e32 v178, v160, v164
	s_and_b64 vcc, s[38:39], vcc
	v_fma_f32 v160, v160, v164, v203
	v_cndmask_b32_e32 v160, v178, v160, vcc
	v_cmp_le_i32_e32 vcc, v173, v169
	v_cmp_eq_u32_e64 s[100:101], v173, v169
	s_xnor_b64 vcc, vcc, s[38:39]
	s_andn2_b64 s[100:101], s[100:101], s[38:39]
	s_or_b64 vcc, vcc, s[100:101]
	v_exp_f32_e32 v156, v156
	v_sub_f32_e32 v157, v171, v157
	v_cndmask_b32_e32 v164, 0, v165, vcc
	v_mul_f32_e32 v164, v164, v179
	v_cmp_eq_u32_e32 vcc, v173, v169
	v_mul_f32_e32 v165, v161, v164
	s_and_b64 vcc, s[38:39], vcc
	v_fma_f32 v161, v161, v164, v203
	v_cndmask_b32_e32 v161, v165, v161, vcc
	v_cmp_le_i32_e32 vcc, v174, v169
	v_cmp_eq_u32_e64 s[100:101], v174, v169
	s_xnor_b64 vcc, vcc, s[38:39]
	s_andn2_b64 s[100:101], s[100:101], s[38:39]
	s_or_b64 vcc, vcc, s[100:101]
	v_exp_f32_e32 v157, v157
	v_sub_f32_e32 v158, v171, v158
	v_cndmask_b32_e32 v164, 0, v166, vcc
	v_mul_f32_e32 v164, v164, v226
	v_cmp_eq_u32_e32 vcc, v174, v169
	v_mul_f32_e32 v165, v162, v164
	s_and_b64 vcc, s[38:39], vcc
	v_fma_f32 v162, v162, v164, v203
	v_cndmask_b32_e32 v162, v165, v162, vcc
	v_sub_f32_e32 v166, v171, v167
	v_exp_f32_e32 v166, v166
	v_cmp_le_i32_e32 vcc, v175, v169
	v_cmp_eq_u32_e64 s[100:101], v175, v169
	s_xnor_b64 vcc, vcc, s[38:39]
	s_andn2_b64 s[100:101], s[100:101], s[38:39]
	s_or_b64 vcc, vcc, s[100:101]
	v_exp_f32_e32 v158, v158
	v_cndmask_b32_e32 v164, 0, v166, vcc
	v_mul_f32_e32 v164, v164, v227
	v_cmp_eq_u32_e32 vcc, v175, v169
	v_mul_f32_e32 v165, v163, v164
	s_and_b64 vcc, s[38:39], vcc
	v_fma_f32 v163, v163, v164, v203
	v_cndmask_b32_e32 v163, v165, v163, vcc
	v_cmp_le_i32_e32 vcc, v200, v169
	v_cmp_eq_u32_e64 s[100:101], v200, v169
	s_xnor_b64 vcc, vcc, s[38:39]
	s_andn2_b64 s[100:101], s[100:101], s[38:39]
	s_or_b64 vcc, vcc, s[100:101]
	s_mov_b32 s94, s92
	s_mov_b32 s95, s92
	v_cndmask_b32_e32 v156, 0, v156, vcc
	v_mul_f32_e32 v156, v156, v228
	v_cmp_eq_u32_e32 vcc, v200, v169
	v_mul_f32_e32 v164, v152, v156
	s_and_b64 vcc, s[38:39], vcc
	v_fma_f32 v152, v152, v156, v203
	v_cndmask_b32_e32 v156, v164, v152, vcc
	v_cmp_le_i32_e32 vcc, v201, v169
	v_cmp_eq_u32_e64 s[100:101], v201, v169
	s_xnor_b64 vcc, vcc, s[38:39]
	s_andn2_b64 s[100:101], s[100:101], s[38:39]
	s_or_b64 vcc, vcc, s[100:101]
	s_mov_b32 s93, s92
	s_nop 0
	v_cndmask_b32_e32 v152, 0, v157, vcc
	v_mul_f32_e32 v152, v152, v229
	v_cmp_eq_u32_e32 vcc, v201, v169
	v_mul_f32_e32 v157, v153, v152
	s_and_b64 vcc, s[38:39], vcc
	v_fma_f32 v152, v153, v152, v203
	v_cndmask_b32_e32 v157, v157, v152, vcc
	v_cmp_le_i32_e32 vcc, v216, v169
	v_cmp_eq_u32_e64 s[100:101], v216, v169
	s_xnor_b64 vcc, vcc, s[38:39]
	s_andn2_b64 s[100:101], s[100:101], s[38:39]
	s_or_b64 vcc, vcc, s[100:101]
	v_cndmask_b32_e32 v152, 0, v158, vcc
	v_mul_f32_e32 v152, v152, v230
	v_cmp_eq_u32_e32 vcc, v216, v169
	v_mul_f32_e32 v153, v154, v152
	s_and_b64 vcc, s[38:39], vcc
	v_fma_f32 v152, v154, v152, v203
	v_cndmask_b32_e32 v158, v153, v152, vcc
	v_sub_f32_e32 v154, v171, v159
	v_exp_f32_e32 v154, v154
	v_cmp_le_i32_e32 vcc, v217, v169
	v_cmp_eq_u32_e64 s[100:101], v217, v169
	s_xnor_b64 vcc, vcc, s[38:39]
	s_andn2_b64 s[100:101], s[100:101], s[38:39]
	s_or_b64 vcc, vcc, s[100:101]
	v_cndmask_b32_e32 v152, 0, v154, vcc
	v_mul_f32_e32 v152, v152, v231
	v_cmp_eq_u32_e32 vcc, v217, v169
	v_mul_f32_e32 v153, v155, v152
	s_and_b64 vcc, s[38:39], vcc
	v_fma_f32 v152, v155, v152, v203
	v_cndmask_b32_e32 v155, v153, v152, vcc
	v_cvt_pk_bf16_f32 v152, v160, v161
	v_cvt_pk_bf16_f32 v153, v162, v163
	v_cvt_pk_bf16_f32 v154, v156, v157
	v_cvt_pk_bf16_f32 v155, v158, v155
	ds_read_b32 v161, v214 offset:384
	v_or_b32_e32 v160, 0x60, v176
	v_mfma_f32_16x16x32_bf16 v[144:147], v[100:103], v[152:155], v[144:147]
	v_mov_b64_e32 v[102:103], s[94:95]
	v_mov_b64_e32 v[100:101], s[92:93]
	s_and_b64 vcc, exec, s[46:47]
	v_mfma_f32_16x16x32_bf16 v[140:143], v[140:143], v[152:155], v[148:151]
	s_nop 2
	v_exp_f32_e32 v148, v171
	v_add_u32_e32 v150, s5, v169
	v_ashrrev_i32_e32 v151, 31, v150
	v_lshlrev_b64 v[150:151], 13, v[150:151]
	v_pk_fma_f32 v[146:147], v[148:149], v[224:225], v[146:147] op_sel_hi:[0,1,1]
	v_pk_fma_f32 v[144:145], v[148:149], v[222:223], v[144:145] op_sel_hi:[0,1,1]
	v_pk_fma_f32 v[142:143], v[148:149], v[220:221], v[142:143] op_sel_hi:[0,1,1]
	v_pk_fma_f32 v[140:141], v[148:149], v[218:219], v[140:141] op_sel_hi:[0,1,1]
	v_lshl_add_u64 v[150:151], v[198:199], 0, v[150:151]
	v_cvt_pk_bf16_f32 v144, v144, v145
	v_cvt_pk_bf16_f32 v145, v146, v147
	v_cvt_pk_bf16_f32 v140, v140, v141
	v_cvt_pk_bf16_f32 v141, v142, v143
	global_store_dwordx2 v[150:151], v[144:145], off
	global_store_dwordx2 v[150:151], v[140:141], off offset:32
	v_lshlrev_b32_e32 v141, 8, v160
	v_mov_b64_e32 v[150:151], s[94:95]
	v_add_u32_e32 v140, s87, v141
	v_mov_b64_e32 v[148:149], s[92:93]
	s_cbranch_vccz .LBB0_536
	s_and_b64 vcc, exec, s[46:47]
	s_cbranch_vccz .LBB0_537
